# v78 + P6 epilogue residual loads de-serialised + SADDR-form LDS-DMA in the P6 K-loop (stack of the two P6 edits)
# speedup vs baseline: 1.0079x; 1.0079x over previous
.LBB0_1058:
	ds_read_b128 v[128:131], v194
	ds_read_b128 v[132:135], v194 offset:1024
	ds_read_b128 v[136:139], v194 offset:2048
	ds_read_b128 v[140:143], v194 offset:3072
	ds_read_b128 v[144:147], v195
	ds_read_b128 v[148:151], v195 offset:1024
	ds_read_b128 v[152:155], v195 offset:2048
	ds_read_b128 v[156:159], v195 offset:3072
	s_add_u32 s2, s0, 0x100
	s_addc_u32 s3, s1, 0
	s_cmpk_eq_i32 s39, 0xa8
	s_cselect_b32 s37, s31, s3
	s_cselect_b32 s36, s30, s2
	s_cselect_b32 s5, s7, s38
	s_cselect_b32 s4, s6, s29
	s_add_i32 m0, s27, 0xc000
	ds_read_b128 v[172:175], v196
	ds_read_b128 v[176:179], v196 offset:1024
	ds_read_b128 v[180:183], v196 offset:2048
	ds_read_b128 v[184:187], v196 offset:3072
	ds_read_b128 v[200:203], v196 offset:4096
	ds_read_b128 v[204:207], v196 offset:5120
	ds_read_b128 v[208:211], v196 offset:6144
	ds_read_b128 v[212:215], v196 offset:7168
	global_load_lds_dwordx4 v168, s[0:1]
	s_add_i32 m0, s27, 0xe000
	s_nop 0
	global_load_lds_dwordx4 v170, s[0:1]
	s_waitcnt vmcnt(8)
	s_waitcnt lgkmcnt(0)
	s_barrier
	s_waitcnt lgkmcnt(0)
	v_mfma_f32_16x16x32_bf16 v[12:15], v[128:131], v[172:175], v[12:15]
	v_mfma_f32_16x16x32_bf16 v[12:15], v[132:135], v[176:179], v[12:15]
	v_mfma_f32_16x16x32_bf16 v[8:11], v[136:139], v[172:175], v[8:11]
	v_mfma_f32_16x16x32_bf16 v[8:11], v[140:143], v[176:179], v[8:11]
	v_mfma_f32_16x16x32_bf16 v[36:39], v[128:131], v[180:183], v[36:39]
	v_mfma_f32_16x16x32_bf16 v[36:39], v[132:135], v[184:187], v[36:39]
	v_mfma_f32_16x16x32_bf16 v[32:35], v[136:139], v[180:183], v[32:35]
	v_mfma_f32_16x16x32_bf16 v[32:35], v[140:143], v[184:187], v[32:35]
	v_mfma_f32_16x16x32_bf16 v[44:47], v[128:131], v[200:203], v[44:47]
	v_mfma_f32_16x16x32_bf16 v[44:47], v[132:135], v[204:207], v[44:47]
	v_mfma_f32_16x16x32_bf16 v[40:43], v[136:139], v[200:203], v[40:43]
	v_mfma_f32_16x16x32_bf16 v[40:43], v[140:143], v[204:207], v[40:43]
	v_mfma_f32_16x16x32_bf16 v[64:67], v[128:131], v[208:211], v[64:67]
	v_mfma_f32_16x16x32_bf16 v[64:67], v[132:135], v[212:215], v[64:67]
	v_mfma_f32_16x16x32_bf16 v[56:59], v[136:139], v[208:211], v[56:59]
	v_mfma_f32_16x16x32_bf16 v[56:59], v[140:143], v[212:215], v[56:59]
	v_mfma_f32_16x16x32_bf16 v[4:7], v[144:147], v[172:175], v[4:7]
	v_mfma_f32_16x16x32_bf16 v[4:7], v[148:151], v[176:179], v[4:7]
	v_mfma_f32_16x16x32_bf16 v[0:3], v[152:155], v[172:175], v[0:3]
	v_mfma_f32_16x16x32_bf16 v[0:3], v[156:159], v[176:179], v[0:3]
	v_mfma_f32_16x16x32_bf16 v[24:27], v[144:147], v[180:183], v[24:27]
	v_mfma_f32_16x16x32_bf16 v[24:27], v[148:151], v[184:187], v[24:27]
	v_mfma_f32_16x16x32_bf16 v[16:19], v[152:155], v[180:183], v[16:19]
	v_mfma_f32_16x16x32_bf16 v[16:19], v[156:159], v[184:187], v[16:19]
	v_mfma_f32_16x16x32_bf16 v[28:31], v[144:147], v[200:203], v[28:31]
	v_mfma_f32_16x16x32_bf16 v[28:31], v[148:151], v[204:207], v[28:31]
	v_mfma_f32_16x16x32_bf16 v[20:23], v[152:155], v[200:203], v[20:23]
	v_mfma_f32_16x16x32_bf16 v[20:23], v[156:159], v[204:207], v[20:23]
	v_mfma_f32_16x16x32_bf16 v[52:55], v[144:147], v[208:211], v[52:55]
	v_mfma_f32_16x16x32_bf16 v[52:55], v[148:151], v[212:215], v[52:55]
	v_mfma_f32_16x16x32_bf16 v[48:51], v[152:155], v[208:211], v[48:51]
	v_mfma_f32_16x16x32_bf16 v[48:51], v[156:159], v[212:215], v[48:51]
	s_barrier
	s_add_i32 s0, s17, s25
	s_mov_b32 m0, s0
	ds_read_b128 v[172:175], v196 offset:16384
	ds_read_b128 v[176:179], v196 offset:17408
	ds_read_b128 v[180:183], v196 offset:18432
	ds_read_b128 v[184:187], v196 offset:19456
	ds_read_b128 v[200:203], v196 offset:20480
	ds_read_b128 v[204:207], v196 offset:21504
	ds_read_b128 v[208:211], v196 offset:22528
	ds_read_b128 v[212:215], v196 offset:23552
	global_load_lds_dwordx4 v162, s[4:5]
	s_add_i32 m0, s0, 0x2000
	s_add_u32 s0, s4, 0x2b0000
	s_addc_u32 s1, s5, 0
	s_add_i32 s40, s55, s25
	global_load_lds_dwordx4 v166, s[4:5]
	s_mov_b32 m0, s40
	s_nop 0
	global_load_lds_dwordx4 v162, s[0:1]
	s_add_i32 m0, s40, 0x2000
	s_nop 0
	global_load_lds_dwordx4 v166, s[0:1]
	s_mov_b32 m0, s27
	s_nop 0
	global_load_lds_dwordx4 v160, s[36:37]
	s_mov_b32 m0, s33
	s_nop 0
	global_load_lds_dwordx4 v164, s[36:37]
	s_waitcnt vmcnt(8)
	s_waitcnt lgkmcnt(0)
	s_barrier
	s_waitcnt lgkmcnt(0)
	v_mfma_f32_16x16x32_bf16 v[76:79], v[128:131], v[172:175], v[76:79]
	v_mfma_f32_16x16x32_bf16 v[76:79], v[132:135], v[176:179], v[76:79]
	v_mfma_f32_16x16x32_bf16 v[72:75], v[136:139], v[172:175], v[72:75]
	v_mfma_f32_16x16x32_bf16 v[72:75], v[140:143], v[176:179], v[72:75]
	v_mfma_f32_16x16x32_bf16 v[92:95], v[128:131], v[180:183], v[92:95]
	v_mfma_f32_16x16x32_bf16 v[92:95], v[132:135], v[184:187], v[92:95]
	v_mfma_f32_16x16x32_bf16 v[88:91], v[136:139], v[180:183], v[88:91]
	v_mfma_f32_16x16x32_bf16 v[88:91], v[140:143], v[184:187], v[88:91]
	v_mfma_f32_16x16x32_bf16 v[108:111], v[128:131], v[200:203], v[108:111]
	v_mfma_f32_16x16x32_bf16 v[108:111], v[132:135], v[204:207], v[108:111]
	v_mfma_f32_16x16x32_bf16 v[104:107], v[136:139], v[200:203], v[104:107]
	v_mfma_f32_16x16x32_bf16 v[104:107], v[140:143], v[204:207], v[104:107]
	v_mfma_f32_16x16x32_bf16 v[124:127], v[128:131], v[208:211], v[124:127]
	v_mfma_f32_16x16x32_bf16 v[124:127], v[132:135], v[212:215], v[124:127]
	v_mfma_f32_16x16x32_bf16 v[120:123], v[136:139], v[208:211], v[120:123]
	v_mfma_f32_16x16x32_bf16 v[120:123], v[140:143], v[212:215], v[120:123]
	v_mfma_f32_16x16x32_bf16 v[68:71], v[144:147], v[172:175], v[68:71]
	v_mfma_f32_16x16x32_bf16 v[68:71], v[148:151], v[176:179], v[68:71]
	v_mfma_f32_16x16x32_bf16 v[60:63], v[152:155], v[172:175], v[60:63]
	v_mfma_f32_16x16x32_bf16 v[60:63], v[156:159], v[176:179], v[60:63]
	v_mfma_f32_16x16x32_bf16 v[84:87], v[144:147], v[180:183], v[84:87]
	v_mfma_f32_16x16x32_bf16 v[84:87], v[148:151], v[184:187], v[84:87]
	v_mfma_f32_16x16x32_bf16 v[80:83], v[152:155], v[180:183], v[80:83]
	v_mfma_f32_16x16x32_bf16 v[80:83], v[156:159], v[184:187], v[80:83]
	v_mfma_f32_16x16x32_bf16 v[100:103], v[144:147], v[200:203], v[100:103]
	v_mfma_f32_16x16x32_bf16 v[100:103], v[148:151], v[204:207], v[100:103]
	v_mfma_f32_16x16x32_bf16 v[96:99], v[152:155], v[200:203], v[96:99]
	v_mfma_f32_16x16x32_bf16 v[96:99], v[156:159], v[204:207], v[96:99]
	v_mfma_f32_16x16x32_bf16 v[116:119], v[144:147], v[208:211], v[116:119]
	v_mfma_f32_16x16x32_bf16 v[116:119], v[148:151], v[212:215], v[116:119]
	v_mfma_f32_16x16x32_bf16 v[112:115], v[152:155], v[208:211], v[112:115]
	v_mfma_f32_16x16x32_bf16 v[112:115], v[156:159], v[212:215], v[112:115]
	s_barrier
	v_add_u32_e32 v140, s56, v193
	v_add_u32_e32 v156, s57, v193
	ds_read_b128 v[128:131], v140
	ds_read_b128 v[132:135], v140 offset:1024
	ds_read_b128 v[136:139], v140 offset:2048
	ds_read_b128 v[140:143], v140 offset:3072
	ds_read_b128 v[144:147], v156
	ds_read_b128 v[148:151], v156 offset:1024
	ds_read_b128 v[152:155], v156 offset:2048
	ds_read_b128 v[156:159], v156 offset:3072
	s_add_u32 s0, s36, 0x2b0000
	s_addc_u32 s1, s37, 0
	s_mov_b32 m0, s46
	ds_read_b128 v[172:175], v196 offset:32768
	ds_read_b128 v[176:179], v196 offset:33792
	ds_read_b128 v[180:183], v196 offset:34816
	ds_read_b128 v[184:187], v196 offset:35840
	ds_read_b128 v[200:203], v196 offset:36864
	ds_read_b128 v[204:207], v196 offset:37888
	ds_read_b128 v[208:211], v196 offset:38912
	ds_read_b128 v[212:215], v196 offset:39936
	global_load_lds_dwordx4 v160, s[0:1]
	s_mov_b32 m0, s47
	s_nop 0
	global_load_lds_dwordx4 v164, s[0:1]
	s_waitcnt vmcnt(8)
	s_waitcnt lgkmcnt(0)
	s_barrier
	s_waitcnt lgkmcnt(0)
	v_mfma_f32_16x16x32_bf16 v[12:15], v[128:131], v[172:175], v[12:15]
	v_mfma_f32_16x16x32_bf16 v[12:15], v[132:135], v[176:179], v[12:15]
	v_mfma_f32_16x16x32_bf16 v[8:11], v[136:139], v[172:175], v[8:11]
	v_mfma_f32_16x16x32_bf16 v[8:11], v[140:143], v[176:179], v[8:11]
	v_mfma_f32_16x16x32_bf16 v[36:39], v[128:131], v[180:183], v[36:39]
	v_mfma_f32_16x16x32_bf16 v[36:39], v[132:135], v[184:187], v[36:39]
	v_mfma_f32_16x16x32_bf16 v[32:35], v[136:139], v[180:183], v[32:35]
	v_mfma_f32_16x16x32_bf16 v[32:35], v[140:143], v[184:187], v[32:35]
	v_mfma_f32_16x16x32_bf16 v[44:47], v[128:131], v[200:203], v[44:47]
	v_mfma_f32_16x16x32_bf16 v[44:47], v[132:135], v[204:207], v[44:47]
	v_mfma_f32_16x16x32_bf16 v[40:43], v[136:139], v[200:203], v[40:43]
	v_mfma_f32_16x16x32_bf16 v[40:43], v[140:143], v[204:207], v[40:43]
	v_mfma_f32_16x16x32_bf16 v[64:67], v[128:131], v[208:211], v[64:67]
	v_mfma_f32_16x16x32_bf16 v[64:67], v[132:135], v[212:215], v[64:67]
	v_mfma_f32_16x16x32_bf16 v[56:59], v[136:139], v[208:211], v[56:59]
	v_mfma_f32_16x16x32_bf16 v[56:59], v[140:143], v[212:215], v[56:59]
	v_mfma_f32_16x16x32_bf16 v[4:7], v[144:147], v[172:175], v[4:7]
	v_mfma_f32_16x16x32_bf16 v[4:7], v[148:151], v[176:179], v[4:7]
	v_mfma_f32_16x16x32_bf16 v[0:3], v[152:155], v[172:175], v[0:3]
	v_mfma_f32_16x16x32_bf16 v[0:3], v[156:159], v[176:179], v[0:3]
	v_mfma_f32_16x16x32_bf16 v[24:27], v[144:147], v[180:183], v[24:27]
	v_mfma_f32_16x16x32_bf16 v[24:27], v[148:151], v[184:187], v[24:27]
	v_mfma_f32_16x16x32_bf16 v[16:19], v[152:155], v[180:183], v[16:19]
	v_mfma_f32_16x16x32_bf16 v[16:19], v[156:159], v[184:187], v[16:19]
	v_mfma_f32_16x16x32_bf16 v[28:31], v[144:147], v[200:203], v[28:31]
	v_mfma_f32_16x16x32_bf16 v[28:31], v[148:151], v[204:207], v[28:31]
	v_mfma_f32_16x16x32_bf16 v[20:23], v[152:155], v[200:203], v[20:23]
	v_mfma_f32_16x16x32_bf16 v[20:23], v[156:159], v[204:207], v[20:23]
	v_mfma_f32_16x16x32_bf16 v[52:55], v[144:147], v[208:211], v[52:55]
	v_mfma_f32_16x16x32_bf16 v[52:55], v[148:151], v[212:215], v[52:55]
	v_mfma_f32_16x16x32_bf16 v[48:51], v[152:155], v[208:211], v[48:51]
	v_mfma_f32_16x16x32_bf16 v[48:51], v[156:159], v[212:215], v[48:51]
	s_barrier
	s_add_i32 s0, s56, s25
	s_add_u32 s98, s4, 0x80
	s_addc_u32 s99, s5, 0
	s_add_u32 s100, s36, 0x80
	s_addc_u32 s101, s37, 0
	s_mov_b32 m0, s0
	ds_read_b128 v[172:175], v196 offset:49152
	ds_read_b128 v[176:179], v196 offset:50176
	ds_read_b128 v[180:183], v196 offset:51200
	ds_read_b128 v[184:187], v196 offset:52224
	ds_read_b128 v[200:203], v196 offset:53248
	ds_read_b128 v[204:207], v196 offset:54272
	ds_read_b128 v[208:211], v196 offset:55296
	ds_read_b128 v[212:215], v196 offset:56320
	global_load_lds_dwordx4 v162, s[98:99]
	s_add_i32 m0, s0, 0x2000
	s_add_u32 s0, s4, 0x2b0080
	s_addc_u32 s1, s5, 0
	s_add_i32 s4, s57, s25
	global_load_lds_dwordx4 v166, s[98:99]
	s_mov_b32 m0, s4
	s_nop 0
	global_load_lds_dwordx4 v162, s[0:1]
	s_add_i32 m0, s4, 0x2000
	s_nop 0
	global_load_lds_dwordx4 v166, s[0:1]
	s_mov_b32 m0, s52
	s_nop 0
	global_load_lds_dwordx4 v160, s[100:101]
	s_mov_b32 m0, s53
	s_nop 0
	global_load_lds_dwordx4 v164, s[100:101]
	s_waitcnt vmcnt(8)
	s_waitcnt lgkmcnt(0)
	s_barrier
	s_waitcnt lgkmcnt(0)
	v_mfma_f32_16x16x32_bf16 v[76:79], v[128:131], v[172:175], v[76:79]
	v_mfma_f32_16x16x32_bf16 v[76:79], v[132:135], v[176:179], v[76:79]
	v_mfma_f32_16x16x32_bf16 v[72:75], v[136:139], v[172:175], v[72:75]
	v_mfma_f32_16x16x32_bf16 v[72:75], v[140:143], v[176:179], v[72:75]
	v_mfma_f32_16x16x32_bf16 v[92:95], v[128:131], v[180:183], v[92:95]
	v_mfma_f32_16x16x32_bf16 v[92:95], v[132:135], v[184:187], v[92:95]
	v_mfma_f32_16x16x32_bf16 v[88:91], v[136:139], v[180:183], v[88:91]
	v_mfma_f32_16x16x32_bf16 v[88:91], v[140:143], v[184:187], v[88:91]
	v_mfma_f32_16x16x32_bf16 v[108:111], v[128:131], v[200:203], v[108:111]
	v_mfma_f32_16x16x32_bf16 v[108:111], v[132:135], v[204:207], v[108:111]
	v_mfma_f32_16x16x32_bf16 v[104:107], v[136:139], v[200:203], v[104:107]
	v_mfma_f32_16x16x32_bf16 v[104:107], v[140:143], v[204:207], v[104:107]
	v_mfma_f32_16x16x32_bf16 v[124:127], v[128:131], v[208:211], v[124:127]
	v_mfma_f32_16x16x32_bf16 v[124:127], v[132:135], v[212:215], v[124:127]
	v_mfma_f32_16x16x32_bf16 v[120:123], v[136:139], v[208:211], v[120:123]
	v_mfma_f32_16x16x32_bf16 v[120:123], v[140:143], v[212:215], v[120:123]
	v_mfma_f32_16x16x32_bf16 v[68:71], v[144:147], v[172:175], v[68:71]
	v_mfma_f32_16x16x32_bf16 v[68:71], v[148:151], v[176:179], v[68:71]
	v_mfma_f32_16x16x32_bf16 v[60:63], v[152:155], v[172:175], v[60:63]
	v_mfma_f32_16x16x32_bf16 v[60:63], v[156:159], v[176:179], v[60:63]
	v_mfma_f32_16x16x32_bf16 v[84:87], v[144:147], v[180:183], v[84:87]
	v_mfma_f32_16x16x32_bf16 v[84:87], v[148:151], v[184:187], v[84:87]
	v_mfma_f32_16x16x32_bf16 v[80:83], v[152:155], v[180:183], v[80:83]
	v_mfma_f32_16x16x32_bf16 v[80:83], v[156:159], v[184:187], v[80:83]
	v_mfma_f32_16x16x32_bf16 v[100:103], v[144:147], v[200:203], v[100:103]
	v_mfma_f32_16x16x32_bf16 v[100:103], v[148:151], v[204:207], v[100:103]
	v_mfma_f32_16x16x32_bf16 v[96:99], v[152:155], v[200:203], v[96:99]
	v_mfma_f32_16x16x32_bf16 v[96:99], v[156:159], v[204:207], v[96:99]
	v_mfma_f32_16x16x32_bf16 v[116:119], v[144:147], v[208:211], v[116:119]
	v_mfma_f32_16x16x32_bf16 v[116:119], v[148:151], v[212:215], v[116:119]
	v_mfma_f32_16x16x32_bf16 v[112:115], v[152:155], v[208:211], v[112:115]
	v_mfma_f32_16x16x32_bf16 v[112:115], v[156:159], v[212:215], v[112:115]
	s_barrier
	s_add_i32 s39, s39, 2
	s_add_u32 s29, s29, 0x100
	s_addc_u32 s38, s38, 0
	s_cmpk_gt_u32 s39, 0xa9
	s_mov_b64 s[0:1], s[2:3]
	s_cbranch_scc0 .LBB0_1058
	s_and_b64 vcc, exec, s[20:21]
	s_cbranch_vccz .LBB0_1061
	s_barrier
